# attention steady loop: K(t+3)/V(t+1) LDS-DMA issued at the top of each step instead of after the QK MFMAs (on top of the prologue change)
# baseline (speedup 1.0000x reference)
.LBB0_148:
	v_lshl_add_u64 v[164:165], v[178:179], 0, s[90:91]
	s_add_i32 m0, s41, s18
	v_lshl_add_u64 v[166:167], v[176:177], 0, s[90:91]
	global_load_lds_dwordx4 v[164:165], off
	s_add_i32 m0, s28, s19
	s_nop 0
	global_load_lds_dwordx4 v[166:167], off
	v_add_u32_e32 v168, s6, v221
	ds_read_b64_tr_b16 v[164:165], v168 offset:24576
	ds_read_b64_tr_b16 v[166:167], v168 offset:25088
	s_waitcnt lgkmcnt(9)
	v_mfma_f32_32x32x16_bf16 v[64:79], v[156:159], v[116:119], v[64:79]
	v_add_f32_e32 v104, v80, v81
	v_add_f32_e32 v104, v82, v104
	v_add_f32_e32 v104, v83, v104
	v_add_f32_e32 v104, v84, v104
	v_add_f32_e32 v104, v85, v104
	v_cvt_pk_bf16_f32 v124, v80, v81
	v_cvt_pk_bf16_f32 v125, v82, v83
	ds_read_b64_tr_b16 v[160:161], v168 offset:28672
	ds_read_b64_tr_b16 v[162:163], v168 offset:29184
	s_waitcnt lgkmcnt(10)
	v_mfma_f32_32x32x16_bf16 v[48:63], v[152:155], v[116:119], v[48:63]
	v_add_f32_e32 v80, v86, v104
	v_add_f32_e32 v80, v87, v80
	v_add_f32_e32 v80, v88, v80
	v_add_f32_e32 v80, v89, v80
	v_cvt_pk_bf16_f32 v126, v84, v85
	v_cvt_pk_bf16_f32 v127, v86, v87
	ds_read_b64_tr_b16 v[152:153], v168 offset:25600
	ds_read_b64_tr_b16 v[154:155], v168 offset:26112
	s_waitcnt lgkmcnt(11)
	v_mfma_f32_32x32x16_bf16 v[64:79], v[148:151], v[108:111], v[64:79]
	v_add_f32_e32 v80, v90, v80
	v_add_f32_e32 v80, v91, v80
	v_add_f32_e32 v80, v92, v80
	v_add_f32_e32 v80, v93, v80
	v_cvt_pk_bf16_f32 v120, v88, v89
	v_cvt_pk_bf16_f32 v121, v90, v91
	ds_read_b64_tr_b16 v[148:149], v168 offset:29696
	ds_read_b64_tr_b16 v[150:151], v168 offset:30208
	s_waitcnt lgkmcnt(12)
	v_mfma_f32_32x32x16_bf16 v[48:63], v[144:147], v[108:111], v[48:63]
	v_add_f32_e32 v80, v94, v80
	v_add_f32_e32 v80, v95, v80
	v_add_f32_e32 v80, v32, v80
	v_add_f32_e32 v80, v33, v80
	v_cvt_pk_bf16_f32 v122, v92, v93
	v_cvt_pk_bf16_f32 v123, v94, v95
	ds_read_b64_tr_b16 v[156:157], v168 offset:26624
	ds_read_b64_tr_b16 v[158:159], v168 offset:27136
	s_waitcnt lgkmcnt(13)
	v_mfma_f32_32x32x16_bf16 v[64:79], v[140:143], v[100:103], v[64:79]
	v_add_f32_e32 v80, v34, v80
	v_add_f32_e32 v80, v35, v80
	v_add_f32_e32 v80, v36, v80
	v_add_f32_e32 v80, v37, v80
	v_cvt_pk_bf16_f32 v112, v32, v33
	v_cvt_pk_bf16_f32 v113, v34, v35
	ds_read_b64_tr_b16 v[144:145], v168 offset:30720
	ds_read_b64_tr_b16 v[146:147], v168 offset:31232
	s_waitcnt lgkmcnt(14)
	v_mfma_f32_32x32x16_bf16 v[48:63], v[132:135], v[100:103], v[48:63]
	v_add_f32_e32 v32, v38, v80
	v_add_f32_e32 v32, v39, v32
	v_add_f32_e32 v32, v40, v32
	v_add_f32_e32 v32, v41, v32
	v_cvt_pk_bf16_f32 v114, v36, v37
	v_cvt_pk_bf16_f32 v115, v38, v39
	ds_read_b64_tr_b16 v[140:141], v168 offset:27648
	ds_read_b64_tr_b16 v[142:143], v168 offset:28160
	s_waitcnt lgkmcnt(14)
	v_mfma_f32_32x32x16_bf16 v[64:79], v[136:139], v[96:99], v[64:79]
	v_add_f32_e32 v32, v42, v32
	v_add_f32_e32 v32, v43, v32
	v_add_f32_e32 v32, v44, v32
	v_add_f32_e32 v32, v45, v32
	v_cvt_pk_bf16_f32 v104, v40, v41
	v_cvt_pk_bf16_f32 v105, v42, v43
	ds_read_b64_tr_b16 v[132:133], v168 offset:31744
	ds_read_b64_tr_b16 v[134:135], v168 offset:32256
	v_mfma_f32_32x32x16_bf16 v[48:63], v[128:131], v[96:99], v[48:63]
	v_add_f32_e32 v32, v46, v32
	v_add_f32_e32 v32, v47, v32
	v_add_f32_e32 v34, 0, v32
	v_cvt_pk_bf16_f32 v106, v44, v45
	v_cvt_pk_bf16_f32 v107, v46, v47
	s_nop 5
	v_max_f32_e32 v32, v65, v65
	v_max_f32_e32 v33, v64, v64
	v_max_f32_e32 v32, v33, v32
	v_max3_f32 v33, v66, v67, v49
	v_max3_f32 v32, v32, v48, v50
	v_max3_f32 v32, v32, v51, v68
	v_max3_f32 v33, v33, v70, v71
	v_max3_f32 v32, v32, v69, v52
	v_max3_f32 v33, v33, v54, v55
	v_max3_f32 v32, v32, v53, v72
	v_max3_f32 v33, v33, v74, v75
	v_max3_f32 v32, v32, v73, v56
	v_max3_f32 v33, v33, v58, v59
	v_max3_f32 v32, v32, v57, v76
	v_max3_f32 v33, v33, v78, v79
	v_max3_f32 v32, v32, v77, v60
	v_max3_f32 v33, v33, v62, v63
	v_max3_f32 v32, v32, v61, v33
	v_mov_b32_e32 v33, v32
	s_nop 1
	v_permlane32_swap_b32_e32 v32, v33
	v_max_f32_e32 v33, v33, v33
	v_max_f32_e32 v32, v32, v32
	v_max_f32_e32 v32, v32, v33
	v_cmp_lt_f32_e32 vcc, s47, v32
	s_cmp_lg_u64 vcc, 0
	v_add_f32_e32 v181, v222, v34
	s_cselect_b64 s[6:7], -1, 0
	s_cbranch_vccnz .LBB0_156

.LBB0_151:
	s_add_i32 s6, s28, 0x2000
	s_cmpk_lg_i32 s28, 0x4000
	s_cselect_b32 s22, s6, 0
	s_add_i32 m0, s28, s18
	s_nop 0
	global_load_lds_dwordx4 v[178:179], off
	s_add_i32 m0, s22, s19
	s_nop 0
	global_load_lds_dwordx4 v[176:177], off
	v_add_u32_e32 v182, s41, v221
	ds_read_b64_tr_b16 v[144:145], v182 offset:24576
	ds_read_b64_tr_b16 v[146:147], v182 offset:25088
	s_waitcnt lgkmcnt(9)
	v_mfma_f32_32x32x16_bf16 v[80:95], v[168:171], v[116:119], v[80:95]
	v_add_f32_e32 v104, v64, v65
	v_add_f32_e32 v104, v66, v104
	v_add_f32_e32 v104, v67, v104
	v_add_f32_e32 v104, v68, v104
	v_add_f32_e32 v104, v69, v104
	v_cvt_pk_bf16_f32 v124, v64, v65
	v_cvt_pk_bf16_f32 v125, v66, v67
	ds_read_b64_tr_b16 v[140:141], v182 offset:28672
	ds_read_b64_tr_b16 v[142:143], v182 offset:29184
	s_waitcnt lgkmcnt(10)
	v_mfma_f32_32x32x16_bf16 v[32:47], v[128:131], v[116:119], v[32:47]
	v_add_f32_e32 v64, v70, v104
	v_add_f32_e32 v64, v71, v64
	v_add_f32_e32 v64, v72, v64
	v_add_f32_e32 v64, v73, v64
	v_cvt_pk_bf16_f32 v126, v68, v69
	v_cvt_pk_bf16_f32 v127, v70, v71
	ds_read_b64_tr_b16 v[132:133], v182 offset:25600
	ds_read_b64_tr_b16 v[134:135], v182 offset:26112
	s_waitcnt lgkmcnt(11)
	v_mfma_f32_32x32x16_bf16 v[80:95], v[164:167], v[108:111], v[80:95]
	v_add_f32_e32 v64, v74, v64
	v_add_f32_e32 v64, v75, v64
	v_add_f32_e32 v64, v76, v64
	v_add_f32_e32 v64, v77, v64
	v_cvt_pk_bf16_f32 v120, v72, v73
	v_cvt_pk_bf16_f32 v121, v74, v75
	ds_read_b64_tr_b16 v[128:129], v182 offset:29696
	ds_read_b64_tr_b16 v[130:131], v182 offset:30208
	s_waitcnt lgkmcnt(12)
	v_mfma_f32_32x32x16_bf16 v[32:47], v[152:155], v[108:111], v[32:47]
	v_add_f32_e32 v64, v78, v64
	v_add_f32_e32 v64, v79, v64
	v_add_f32_e32 v64, v48, v64
	v_add_f32_e32 v64, v49, v64
	v_cvt_pk_bf16_f32 v122, v76, v77
	v_cvt_pk_bf16_f32 v123, v78, v79
	ds_read_b64_tr_b16 v[172:173], v182 offset:26624
	ds_read_b64_tr_b16 v[174:175], v182 offset:27136
	s_waitcnt lgkmcnt(13)
	v_mfma_f32_32x32x16_bf16 v[80:95], v[160:163], v[100:103], v[80:95]
	v_add_f32_e32 v64, v50, v64
	v_add_f32_e32 v64, v51, v64
	v_add_f32_e32 v64, v52, v64
	v_add_f32_e32 v64, v53, v64
	v_cvt_pk_bf16_f32 v112, v48, v49
	v_cvt_pk_bf16_f32 v113, v50, v51
	ds_read_b64_tr_b16 v[168:169], v182 offset:30720
	ds_read_b64_tr_b16 v[170:171], v182 offset:31232
	s_waitcnt lgkmcnt(14)
	v_mfma_f32_32x32x16_bf16 v[32:47], v[148:151], v[100:103], v[32:47]
	v_add_f32_e32 v48, v54, v64
	v_add_f32_e32 v48, v55, v48
	v_add_f32_e32 v48, v56, v48
	v_add_f32_e32 v48, v57, v48
	v_cvt_pk_bf16_f32 v114, v52, v53
	v_cvt_pk_bf16_f32 v115, v54, v55
	ds_read_b64_tr_b16 v[164:165], v182 offset:27648
	ds_read_b64_tr_b16 v[166:167], v182 offset:28160
	s_waitcnt lgkmcnt(14)
	v_mfma_f32_32x32x16_bf16 v[80:95], v[156:159], v[96:99], v[80:95]
	v_add_f32_e32 v48, v58, v48
	v_add_f32_e32 v48, v59, v48
	v_add_f32_e32 v48, v60, v48
	v_add_f32_e32 v48, v61, v48
	v_cvt_pk_bf16_f32 v104, v56, v57
	v_cvt_pk_bf16_f32 v105, v58, v59
	ds_read_b64_tr_b16 v[160:161], v182 offset:31744
	ds_read_b64_tr_b16 v[162:163], v182 offset:32256
	v_mfma_f32_32x32x16_bf16 v[32:47], v[136:139], v[96:99], v[32:47]
	v_add_f32_e32 v48, v62, v48
	v_add_f32_e32 v48, v63, v48
	v_add_f32_e32 v48, 0, v48
	v_cvt_pk_bf16_f32 v106, v60, v61
	v_cvt_pk_bf16_f32 v107, v62, v63
	v_max_f32_e32 v49, v81, v81
	v_max_f32_e32 v50, v80, v80
	v_max_f32_e32 v49, v50, v49
	s_nop 3
	v_max3_f32 v50, v82, v83, v33
	v_max3_f32 v49, v49, v32, v34
	v_max3_f32 v49, v49, v35, v84
	v_max3_f32 v50, v50, v86, v87
	v_max3_f32 v49, v49, v85, v36
	v_max3_f32 v50, v50, v38, v39
	v_max3_f32 v49, v49, v37, v88
	v_max3_f32 v50, v50, v90, v91
	v_max3_f32 v49, v49, v89, v40
	v_max3_f32 v50, v50, v42, v43
	v_max3_f32 v49, v49, v41, v92
	v_max3_f32 v50, v50, v94, v95
	v_max3_f32 v49, v49, v93, v44
	v_max3_f32 v50, v50, v46, v47
	v_add_f32_e32 v222, v181, v48
	v_max3_f32 v48, v49, v45, v50
	v_mov_b32_e32 v49, v48
	s_nop 1
	v_permlane32_swap_b32_e32 v48, v49
	v_max_f32_e32 v49, v49, v49
	v_max_f32_e32 v48, v48, v48
	v_max_f32_e32 v48, v48, v49
	v_cmp_lt_f32_e32 vcc, s47, v48
	s_cmp_lg_u64 vcc, 0
	s_cselect_b64 s[6:7], -1, 0
	s_cbranch_vccnz .LBB0_159
